# P3 sample-row tasks run on the non-chain workgroups 64..191 before the P2->P3 barrier (while they would idle waiting for the mLSTM chains); no sample tasks after the scan
# baseline (speedup 1.0000x reference)
; __device__ __forceinline__ void rwkv_prep_tile(const Params& p, LAS unsigned char* lds, int tile) {
;     unsigned char* ws = p.ws;
;     LAS h16* RS = (LAS h16*)lds;
;     const int tid = threadIdx.x, lane = tid & 63, wave = tid >> 6, fr = lane & 15, fq = lane >> 4;
;     const h16* PROJ = (const h16*)(ws + OFF_PROJ16);
;     const float* mu = p.in[15];
;     const int row0 = tile * 32;
;     const int h = wave;
;     const h16* LW = (const h16*)(ws + OFF_LW); const h16* LA = (const h16*)(ws + OFF_LA); const h16* LG = (const h16*)(ws + OFF_LG);
;     auto finish_item = [&](const h16x8 cur, const float (&prev)[8], const f32x4 m0, const f32x4 m1, int i, int row, int c) {
;         h16x8 o;
;         const bool is_tanh = (c >= 1536 && c < 1600), is_sig = (c >= 1664);
;         const float act_scale = is_tanh ? 2.f : 1.f;
; #pragma unroll
;         for (int j = 0; j < 8; ++j) {
;             const float pj = (float)cur[j], mj = j < 4 ? m0[j] : m1[j - 4];
;             float rs = pj + mj * (prev[j] - pj);
;             const float sg = sigm(act_scale * rs);
;             rs = is_tanh ? 2.f * sg - 1.f : (is_sig ? sg : rs);
;             o[j] = (h16)rs;
;         }
;         *(LAS h16x8*)(RS + i * 1800 + c) = o;
;         float* so = nullptr;
;         if (row < MP) { if ((row & (SEQ - 1)) == SEQ - 1) so = p.out + O_PSH + (size_t)(row >> 11) * RWW + c; }
;         else so = p.out + O_SSH + (size_t)(row - MP) * RWW + c;
;         if (so) {
;             f32x4 a, b;
; #pragma unroll
;             for (int j = 0; j < 4; ++j) { a[j] = (float)cur[j]; b[j] = (float)cur[4 + j]; }
;             *(f32x4*)so = a; *(f32x4*)(so + 4) = b;
;         }
;     };
; __device__ __forceinline__ void p2_mixprep(const Params& p, LAS unsigned char* lds) {
;     const int nb = gridDim.x, bid = blockIdx.x;
;     if (bid < 64) {
;         const int b = bid >> 3, h = bid & 7;
;         MlChain ch; ch.rowbase = b * SEQ; ch.T = SEQ; ch.h = h; ch.C0 = nullptr; ch.n0 = nullptr; ch.m0 = nullptr; ch.conv0 = nullptr;
;         ch.Cout = p.out + O_PC + (size_t)bid * 4096; ch.nout = p.out + O_PN + (size_t)bid * 64; ch.mout = p.out + O_PM + bid; ch.convout = p.out + O_PCONV + (size_t)b * 3072;
;         mlstm_chain(p, lds, ch);
;         return;
;     }
;     const int w = bid - 64, nw = nb - 64;
;     for (int tile = w; tile < MALL / 32; tile += nw) rwkv_prep_tile(p, lds, tile);
.LBB0_113:
	s_mov_b32 s101, 0
	s_or_b64 exec, exec, s[0:1]
	s_cmp_gt_i32 s2, 63
	s_mov_b64 s[0:1], -1
	s_barrier
	s_cbranch_scc0 .LBB0_199
	s_sub_i32 s3, s2, 64
	s_sub_i32 s34, s33, 64
	s_cmpk_gt_u32 s2, 0x243
	s_cbranch_scc1 .LBB0_170
	v_and_b32_e32 v4, 0x3c0, v132
	s_movk_i32 s26, 0xe10
	v_lshl_or_b32 v7, v144, 2, v4
	v_mad_u32_u24 v1, v131, s26, 0
	v_lshlrev_b32_e32 v4, 1, v7
	v_add_u32_e32 v135, v1, v140
	v_add_u32_e32 v3, 0xe100, v1
	v_add_u32_e32 v145, v1, v4
	v_mbcnt_hi_u32_b32 v1, -1, v225
	v_and_b32_e32 v6, 64, v1
	v_add_u32_e32 v139, v3, v140
	v_add_u32_e32 v227, v3, v4
	v_xor_b32_e32 v3, 16, v1
	v_add_u32_e32 v6, 64, v6
	v_cmp_lt_i32_e32 vcc, v3, v6
	v_mov_b32_e32 v151, 0
	v_mov_b32_e32 v141, v151
	v_cndmask_b32_e32 v3, v1, v3, vcc
	v_lshlrev_b32_e32 v228, 2, v3
	v_xor_b32_e32 v3, 32, v1
	v_cmp_lt_i32_e32 vcc, v3, v6
	v_lshl_add_u64 v[12:13], s[82:83], 0, v[140:141]
	s_mov_b64 s[0:1], 0x1988000
	v_lshlrev_b32_e32 v5, 7, v132
	v_cndmask_b32_e32 v1, v1, v3, vcc
	v_lshl_add_u64 v[14:15], v[12:13], 0, s[0:1]
	s_mov_b64 s[0:1], 0x1998000
	v_and_b32_e32 v0, 0x1e780, v5
	v_lshlrev_b32_e32 v229, 2, v1
	v_lshl_add_u64 v[16:17], v[12:13], 0, s[0:1]
	v_mov_b32_e32 v1, v151
	v_lshlrev_b32_e32 v2, 1, v0
	v_lshl_add_u64 v[152:153], v[14:15], 0, v[0:1]
	v_lshl_add_u64 v[154:155], v[16:17], 0, v[0:1]
	v_or_b32_e32 v0, 0x1000, v0
	v_lshl_add_u64 v[156:157], v[14:15], 0, v[0:1]
	v_lshl_add_u64 v[158:159], v[16:17], 0, v[0:1]
	v_or_b32_e32 v0, 0x1800, v5
	s_mov_b64 s[0:1], 0x19a8000
	v_lshl_add_u64 v[160:161], v[14:15], 0, v[0:1]
	v_lshl_add_u64 v[162:163], v[16:17], 0, v[0:1]
	v_lshl_add_u64 v[0:1], v[12:13], 0, s[0:1]
	v_mov_b32_e32 v3, v151
	v_mov_b32_e32 v5, 0x3000
	v_lshl_add_u64 v[168:169], v[0:1], 0, v[2:3]
	v_or_b32_e32 v14, 0x1000, v2
	v_mov_b32_e32 v15, v151
	v_or_b32_e32 v2, 0x2000, v2
	v_lshl_or_b32 v16, v132, 8, v5
	v_mov_b32_e32 v17, v151
	s_mov_b64 s[0:1], 0x19a8040
	v_readlane_b32 s36, v253, 20
	v_lshl_add_u64 v[170:171], v[0:1], 0, v[14:15]
	v_lshl_add_u64 v[172:173], v[0:1], 0, v[2:3]
	v_lshl_add_u64 v[174:175], v[0:1], 0, v[16:17]
	v_lshl_add_u64 v[0:1], v[12:13], 0, s[0:1]
	s_mov_b64 s[0:1], 0x19a8080
	v_readlane_b32 s50, v253, 34
	v_lshl_add_u64 v[176:177], v[0:1], 0, v[14:15]
	v_lshl_add_u64 v[178:179], v[0:1], 0, v[2:3]
	v_lshl_add_u64 v[0:1], v[12:13], 0, s[0:1]
	s_mov_b64 s[0:1], 0x19a80c0
	v_readlane_b32 s51, v253, 35
	s_add_u32 s16, s50, 0x2080000
	v_lshl_add_u64 v[180:181], v[0:1], 0, v[14:15]
	v_lshl_add_u64 v[182:183], v[0:1], 0, v[2:3]
	v_lshl_add_u64 v[0:1], v[12:13], 0, s[0:1]
	s_addc_u32 s17, s51, 0
	v_lshl_add_u64 v[184:185], v[0:1], 0, v[14:15]
	v_lshl_add_u64 v[186:187], v[0:1], 0, v[2:3]
	v_lshlrev_b32_e32 v0, 2, v7
	v_mov_b32_e32 v1, v151
	s_add_u32 s18, s50, 0x646b100
	v_lshl_add_u64 v[188:189], s[74:75], 0, v[0:1]
	v_lshl_add_u64 v[190:191], s[64:65], 0, v[0:1]
	v_lshl_add_u64 v[192:193], s[68:69], 0, v[0:1]
	v_lshl_add_u64 v[194:195], s[76:77], 0, v[0:1]
	v_lshl_add_u64 v[196:197], s[78:79], 0, v[0:1]
	v_lshlrev_b32_e32 v0, 2, v142
	s_addc_u32 s19, s51, 0
	v_lshlrev_b32_e32 v150, 3, v144
	v_or_b32_e32 v6, 16, v7
	v_or_b32_e32 v8, 32, v7
	v_or_b32_e32 v10, 48, v7
	v_readlane_b32 s37, v253, 21
	v_readlane_b32 s38, v253, 22
	v_readlane_b32 s39, v253, 23
	v_readlane_b32 s40, v253, 24
	v_readlane_b32 s41, v253, 25
	v_readlane_b32 s42, v253, 26
	v_readlane_b32 s43, v253, 27
	v_readlane_b32 s44, v253, 28
	v_readlane_b32 s45, v253, 29
	v_readlane_b32 s46, v253, 30
	v_readlane_b32 s47, v253, 31
	v_readlane_b32 s48, v253, 32
	v_readlane_b32 s49, v253, 33
	v_mov_b32_e32 v5, v151
	v_lshl_add_u64 v[0:1], s[82:83], 0, v[0:1]
	s_mov_b64 s[0:1], 0x1aec800
	s_add_u32 s24, s50, 0x429c100
	v_or_b32_e32 v137, 16, v131
	v_mov_b32_e32 v143, v151
	v_cmp_eq_u32_e64 s[6:7], 0, v144
	s_movk_i32 s27, 0x1000
	v_lshl_add_u64 v[164:165], v[156:157], 0, 64
	v_lshl_add_u64 v[166:167], v[158:159], 0, 64
	v_lshl_add_u64 v[198:199], s[16:17], 0, v[4:5]
	v_lshl_add_u64 v[200:201], v[0:1], 0, s[0:1]
	s_addc_u32 s25, s51, 0
	v_lshl_add_u64 v[202:203], s[86:87], 0, v[150:151]
	v_add_u32_e32 v141, 0x200, v132
	v_lshl_add_u32 v230, v132, 4, 0
	v_add_u32_e32 v231, 0x1000, v224
	v_add_u32_e32 v232, 0x600, v132
	v_add_u32_e32 v233, 0x3000, v224
	v_or_b32_e32 v234, 0x400, v132
	v_or_b32_e32 v235, 0x2000, v224
	s_movk_i32 s28, 0xe0
	s_movk_i32 s29, 0x1e00
	s_movk_i32 s30, 0x1c00
	s_movk_i32 s31, 0xcf
	s_mov_b32 s35, 0xbfb8aa3b
	s_movk_i32 s36, 0x3fff
	s_movk_i32 s37, 0x7ff
	s_movk_i32 s38, 0x700
	s_movk_i32 s39, 0x19ff
	s_mov_b32 s40, 0x24924925
	s_movk_i32 s41, 0xf200
	s_mov_b32 s42, 0x124924a
	s_movk_i32 s43, 0xc0
	s_movk_i32 s44, 0xe00
	s_mov_b32 s45, 0x800000
	s_mov_b32 s46, 0x3f317217
	s_mov_b32 s47, 0x7f800000
	s_movk_i32 s48, 0x300
	s_mov_b32 s49, 0xf800000
	v_mov_b32_e32 v236, 0x260
	v_lshlrev_b32_e32 v204, 1, v6
	v_lshlrev_b32_e32 v206, 1, v8
	v_lshlrev_b32_e32 v208, 1, v10
	v_mov_b32_e32 v237, 0x41b17218
	s_mov_b32 s50, s3
	s_branch .LBB0_117

; __device__ __forceinline__ void p2_mixprep(const Params& p, LAS unsigned char* lds) {
;     ...
;     for (int tile = w; tile < MALL / 32; tile += nw) rwkv_prep_tile(p, lds, tile);
;     for (int i = w * 8 + (int)(threadIdx.x >> 6); i < MS * 8; i += nw * 8) mlstm_sample_task(p, i >> 3, i & 7);
;     __syncthreads();
;     late_transposes(p, lds, w, nw);
.LBB0_289:
	s_cmpk_lg_i32 s33, 0x100
	s_cbranch_scc1 .Lsf_normal0
	s_cmpk_lt_u32 s2, 64
	s_cbranch_scc1 .Lsf_normal0
	s_cmp_eq_u32 s101, 2
	s_cbranch_scc1 .Lsf_normal
	s_waitcnt vmcnt(0) lgkmcnt(0)
	s_barrier
	v_cmp_eq_u32_e32 vcc, 0, v132
	s_and_saveexec_b64 s[98:99], vcc
	s_cbranch_execz .Lsf_d1
	buffer_wbl2 sc1
	s_waitcnt vmcnt(0)
	v_mov_b32_e32 v4, 0x1b6fa80
	v_mov_b32_e32 v5, 1
	global_atomic_add v4, v5, s[82:83]
.Lsf_dpoll:
	global_load_dword v6, v4, s[82:83] sc1
	s_waitcnt vmcnt(0)
	v_readfirstlane_b32 s97, v6
	s_cmpk_lt_u32 s97, 0xc0
	s_cbranch_scc0 .Lsf_d0
	s_sleep 1
	s_branch .Lsf_dpoll
.Lsf_d0:
	buffer_inv sc1
	s_waitcnt vmcnt(0)
.Lsf_d1:
	s_or_b64 exec, exec, s[98:99]
	s_barrier
	s_mov_b32 s101, 1
	s_mov_b64 s[0:1], exec
	s_branch .LBB0_308
.Lsf_normal0:
	s_mov_b32 s101, 0

; #define LAS __attribute__((address_space(3)))
; __device__ __forceinline__ void rwkv_scan_prompt(const Params& p, LAS unsigned char* lds, int bh, int rq) {
;     constexpr int TC = 32, NCH = SEQ / TC, NPIECE = TC * 48 / 256;
;     unsigned char* ws = p.ws;
;     LAS float* OPS = (LAS float*)lds;
;     LAS float* RKB = (LAS float*)(lds + 2 * TC * 6 * 64 * 4);
;     const int tid = threadIdx.x, lane = tid & 63, wave = tid >> 6;
;     const int b = bh >> 3, h = bh & 7, rowbase = b * SEQ;
;     const h16* OPSG = (const h16*)(ws + OFF_OPS16);
;     const float* RKS = (const float*)(ws + OFF_RKS);
;     float* YRAW = (float*)(ws + OFF_YRAW);
;     const int rr = lane >> 4, cg_ = lane & 15, rloc = (wave & 3) * 4 + rr;
;     const int ltid = tid - 256;
;     f32x4 S = {0.f, 0.f, 0.f, 0.f};
;     h16x8 pre[NPIECE]; float prk = 0.f;
;     auto issue_chunk = [&](int c) {
; #pragma unroll
;         for (int i = 0; i < NPIECE; ++i) {
;             const int piece = ltid + 256 * i, tk = piece / 48, q = piece % 48, vec = q >> 3, c8 = q & 7;
;             pre[i] = *(const h16x8*)(OPSG + (((size_t)(rowbase + c * TC + tk) * 8 + h) * 6 + vec) * 64 + c8 * 8);
;         }
;         if (ltid < TC) prk = RKS[(size_t)(rowbase + c * TC + ltid) * 8 + h];
;     };
;     auto store_chunk = [&](int buf) {
; #pragma unroll
;         for (int i = 0; i < NPIECE; ++i) {
;             const int piece = ltid + 256 * i, tk = piece / 48, q = piece % 48, vec = q >> 3, c8 = q & 7;
;             const h16x8 v = pre[i];
;             f32x4 a, bb;
; #pragma unroll
;             for (int j = 0; j < 4; ++j) { a[j] = (float)v[j]; bb[j] = (float)v[4 + j]; }
;             if (vec == 1) {
; #pragma unroll
;                 for (int j = 0; j < 4; ++j) { a[j] = __expf(a[j]); bb[j] = __expf(bb[j]); }
;             }
;             LAS float* d = OPS + ((buf * TC + tk) * 6 + vec) * 64 + c8 * 8;
;             *(LAS f32x4*)d = a; *(LAS f32x4*)(d + 4) = bb;
;         }
;         if (ltid < TC) RKB[buf * TC + ltid] = prk;
;     };
;     if (wave >= 4) { issue_chunk(0); store_chunk(0); issue_chunk(1); }
.LBB0_308:
	s_or_b64 exec, exec, s[0:1]
	s_cmpk_lt_i32 s2, 0x100
	s_movk_i32 s0, 0x100
	s_cselect_b64 s[76:77], -1, 0
	s_cmpk_gt_i32 s2, 0xff
	v_lshlrev_b32_e32 v36, 2, v131
	v_cmp_eq_u32_e64 s[4:5], 15, v131
	v_cmp_eq_u32_e64 s[6:7], 0, v131
	v_cmp_eq_u32_e64 s[8:9], 1, v131
	v_cmp_eq_u32_e64 s[10:11], 2, v131
	v_cmp_eq_u32_e64 s[12:13], 3, v131
	v_cmp_eq_u32_e64 s[14:15], 4, v131
	v_cmp_eq_u32_e64 s[16:17], 5, v131
	v_cmp_eq_u32_e64 s[18:19], 6, v131
	v_cmp_eq_u32_e64 s[20:21], 7, v131
	v_cmp_eq_u32_e64 s[22:23], 8, v131
	v_cmp_eq_u32_e64 s[24:25], 9, v131
	v_cmp_eq_u32_e64 s[26:27], 10, v131
	v_cmp_eq_u32_e64 s[28:29], 11, v131
	v_cmp_eq_u32_e64 s[30:31], 12, v131
	v_cmp_eq_u32_e64 s[34:35], 13, v131
	v_cmp_eq_u32_e64 s[36:37], 14, v131
	v_lshlrev_b32_e32 v52, 4, v131
	s_barrier
	s_cbranch_scc1 .LBB0_360
	s_cmp_eq_u32 s101, 1
	s_cbranch_scc1 .LBB0_360
	v_add_u16_e32 v3, 0x100, v132
	v_mul_u32_u24_e32 v4, 0x556, v3
	v_lshrrev_b32_e32 v57, 16, v4
	v_mul_lo_u16_e32 v4, 48, v57
	v_sub_u16_e32 v63, v3, v4
	v_lshlrev_b32_e32 v3, 3, v63
	v_and_b32_e32 v46, 56, v3
	v_add_u16_e32 v3, 0x200, v132
	v_mul_u32_u24_e32 v4, 0x556, v3
	v_lshrrev_b32_e32 v65, 16, v4
	v_subrev_co_u32_e32 v37, vcc, 0x100, v132
	v_cmp_gt_u32_e64 s[38:39], s0, v132
	s_mov_b32 s0, 0xaaab
	v_mul_lo_u16_e32 v4, 48, v65
	v_mul_u32_u24_sdwa v1, v37, s0 dst_sel:DWORD dst_unused:UNUSED_PAD src0_sel:WORD_0 src1_sel:DWORD
	v_sub_u16_e32 v67, v3, v4
	v_lshrrev_b32_e32 v47, 21, v1
	v_mul_u32_u24_e32 v2, 0x556, v132
	v_lshlrev_b32_e32 v3, 3, v67
	v_mul_lo_u16_e32 v1, 48, v47
	v_lshrrev_b32_e32 v51, 16, v2
	v_and_b32_e32 v50, 56, v3
	v_add_u16_e32 v3, 0x300, v132
	v_sub_u16_e32 v1, v37, v1
	v_mul_lo_u16_e32 v2, 48, v51
	v_mul_u32_u24_e32 v4, 0x556, v3
	v_lshrrev_b32_e32 v38, 3, v1
	v_lshlrev_b32_e32 v1, 3, v1
	v_sub_u16_e32 v2, v132, v2
	v_lshrrev_b32_e32 v108, 16, v4
	v_and_b32_e32 v1, 56, v1
	v_lshrrev_b32_e32 v42, 3, v2
	v_lshlrev_b32_e32 v2, 3, v2
	v_mul_lo_u16_e32 v4, 48, v108
	v_mul_u32_u24_e32 v5, 6, v47
	v_and_b32_e32 v2, 56, v2
	v_sub_u16_e32 v109, v3, v4
	v_add_lshl_u32 v5, v5, v38, 8
	v_lshlrev_b32_e32 v6, 2, v1
	s_movk_i32 s0, 0x556
	v_lshlrev_b32_e32 v3, 3, v109
	v_or_b32_e32 v4, 0x400, v132
	v_add3_u32 v111, 0, v5, v6
	v_mad_u32_u24 v5, v51, 6, v42
	v_lshl_add_u32 v112, v2, 2, 0
	v_lshrrev_b32_e32 v44, 3, v63
	v_and_b32_e32 v56, 56, v3
	v_mul_u32_u24_sdwa v3, v4, s0 dst_sel:DWORD dst_unused:UNUSED_PAD src0_sel:WORD_0 src1_sel:DWORD
	v_lshl_add_u32 v113, v5, 8, v112
	v_mul_u32_u24_e32 v5, 6, v57
	v_lshrrev_b32_e32 v110, 16, v3
	v_add_lshl_u32 v5, v5, v44, 8
	v_lshlrev_b32_e32 v6, 2, v46
	v_lshrrev_b32_e32 v48, 3, v67
	v_mul_lo_u16_e32 v3, 48, v110
	v_add3_u32 v114, 0, v5, v6
	v_mul_u32_u24_e32 v5, 6, v65
	v_sub_u16_e32 v3, v4, v3
	v_add_lshl_u32 v5, v5, v48, 8
	v_lshlrev_b32_e32 v6, 2, v50
	v_lshrrev_b32_e32 v54, 3, v109
	v_lshrrev_b32_e32 v58, 3, v3
	v_lshlrev_b32_e32 v3, 3, v3
	v_add3_u32 v115, 0, v5, v6
	v_mul_u32_u24_e32 v5, 6, v108
	v_and_b32_e32 v3, 56, v3
	v_add_lshl_u32 v5, v5, v54, 8
	v_lshlrev_b32_e32 v6, 2, v56
	v_add3_u32 v116, 0, v5, v6
	v_mad_u32_u24 v5, v110, 6, v58
	v_lshl_add_u32 v117, v3, 2, 0
	v_lshl_add_u32 v118, v5, 8, v117
	v_mul_i32_i24_e32 v5, 0x2aab, v37
	v_mov_b32_e32 v6, 3
	v_ashrrev_i16_sdwa v7, v6, v5 dst_sel:DWORD dst_unused:UNUSED_PAD src0_sel:DWORD src1_sel:WORD_1
	v_lshrrev_b32_e32 v5, 31, v5
	v_add_u16_e32 v127, v7, v5
	v_mul_lo_u16_e32 v5, 48, v127
	v_sub_u16_e32 v5, v37, v5
	v_ashrrev_i32_sdwa v60, v6, sext(v5) dst_sel:DWORD dst_unused:UNUSED_PAD src0_sel:DWORD src1_sel:WORD_0
	v_lshlrev_b32_sdwa v5, v6, sext(v5) dst_sel:DWORD dst_unused:UNUSED_PAD src0_sel:DWORD src1_sel:WORD_0
	v_or_b32_e32 v6, 0x100, v132
	v_mul_u32_u24_sdwa v7, v6, s0 dst_sel:DWORD dst_unused:UNUSED_PAD src0_sel:WORD_0 src1_sel:DWORD
	v_lshrrev_b32_e32 v137, 16, v7
	v_mul_lo_u16_e32 v7, 48, v137
	v_sub_u16_e32 v139, v6, v7
	v_lshlrev_b32_e32 v6, 3, v139
	v_and_b32_e32 v62, 56, v6
	v_or_b32_e32 v6, 0x200, v132
	v_mul_u32_u24_sdwa v7, v6, s0 dst_sel:DWORD dst_unused:UNUSED_PAD src0_sel:WORD_0 src1_sel:DWORD
	v_lshrrev_b32_e32 v141, 16, v7
	v_mul_lo_u16_e32 v7, 48, v141
	v_sub_u16_e32 v143, v6, v7
	v_mov_b32_e32 v41, 0
	v_lshlrev_b32_e32 v6, 3, v143
	v_lshlrev_b32_e32 v40, 1, v1
	v_and_b32_e32 v64, 56, v6
	v_or_b32_e32 v6, 0x300, v132
	v_lshl_add_u64 v[68:69], s[86:87], 0, v[40:41]
	v_lshlrev_b32_e32 v40, 1, v2
	v_mul_u32_u24_sdwa v7, v6, s0 dst_sel:DWORD dst_unused:UNUSED_PAD src0_sel:WORD_0 src1_sel:DWORD
	v_lshl_add_u64 v[70:71], s[86:87], 0, v[40:41]
	v_lshlrev_b32_e32 v40, 1, v46
	v_lshrrev_b32_e32 v145, 16, v7
	v_lshl_add_u64 v[72:73], s[86:87], 0, v[40:41]
	v_lshlrev_b32_e32 v40, 1, v50
	v_mul_lo_u16_e32 v7, 48, v145
	v_lshl_add_u64 v[74:75], s[86:87], 0, v[40:41]
	v_lshlrev_b32_e32 v40, 1, v56
	v_readlane_b32 s60, v253, 20
	s_mov_b32 s0, 0x5555556
	s_add_i32 s3, 0, 0x18000
	v_and_b32_e32 v5, 56, v5
	v_sub_u16_e32 v147, v6, v7
	v_lshl_add_u64 v[76:77], s[86:87], 0, v[40:41]
	v_lshlrev_b32_e32 v40, 1, v3
	v_mov_b32_e32 v53, v41
	v_readlane_b32 s74, v253, 34
	v_readlane_b32 s75, v253, 35
	v_mul_hi_u32 v1, v4, s0
	v_bfe_u32 v0, v132, 4, 4
	v_lshl_add_u32 v119, v37, 2, s3
	v_add_u32_e32 v126, s3, v36
	s_movk_i32 s3, 0x120
	v_lshlrev_b32_e32 v6, 3, v147
	s_add_u32 s84, s82, 0x1aec800
	v_lshl_add_u64 v[78:79], s[86:87], 0, v[40:41]
	v_lshlrev_b32_e32 v40, 1, v5
	v_lshl_add_u64 v[2:3], s[74:75], 0, v[52:53]
	s_mov_b64 s[58:59], 0x419c100
	v_or_b32_e32 v148, 64, v1
	v_mov_b32_e32 v1, 64
	v_mov_b32_e32 v39, v41
	v_mov_b32_e32 v43, v41
	v_mov_b32_e32 v45, v41
	v_mov_b32_e32 v49, v41
	v_mov_b32_e32 v55, v41
	v_mov_b32_e32 v59, v41
	v_cmp_gt_u32_e64 s[40:41], 32, v37
	v_cmp_ne_u32_e64 s[42:43], 1, v38
	s_mov_b32 s1, 0
	v_cmp_ne_u32_e64 s[44:45], 1, v42
	v_cmp_ne_u32_e64 s[46:47], 1, v44
	v_cmp_ne_u32_e64 s[48:49], 1, v48
	v_cmp_ne_u32_e64 s[50:51], 1, v54
	v_cmp_ne_u32_e64 s[52:53], 1, v58
	v_add_u32_e32 v120, 32, v47
	v_add_u32_e32 v121, 32, v57
	v_add_u32_e32 v122, 32, v65
	v_add_u32_e32 v123, 32, v108
	v_add_u32_e32 v124, 32, v110
	v_add_u32_e32 v125, 0xffffff20, v132
	v_cmp_ne_u32_e64 s[54:55], 1, v60
	v_lshl_add_u32 v129, v5, 2, 0
	v_cmp_gt_u32_e64 s[56:57], s3, v132
	v_ashrrev_i32_e32 v61, 31, v60
	v_mul_u32_u24_e32 v135, 0x600, v131
	v_and_b32_e32 v66, 56, v6
	s_addc_u32 s85, s83, 0
	v_lshl_add_u64 v[80:81], s[86:87], 0, v[40:41]
	v_lshl_add_u64 v[82:83], v[2:3], 0, s[58:59]
	v_add_u32_e32 v53, 0xffffff40, v132
	v_or_b32_e32 v149, 64, v51
	v_add_u32_sdwa v150, sext(v127), v1 dst_sel:DWORD dst_unused:UNUSED_PAD src0_sel:WORD_0 src1_sel:DWORD
	v_lshlrev_b32_e32 v84, 2, v0
	s_mov_b32 s3, s2
	v_readlane_b32 s61, v253, 21
	v_readlane_b32 s62, v253, 22
	v_readlane_b32 s63, v253, 23
	v_readlane_b32 s64, v253, 24
	v_readlane_b32 s65, v253, 25
	v_readlane_b32 s66, v253, 26
	v_readlane_b32 s67, v253, 27
	v_readlane_b32 s68, v253, 28
	v_readlane_b32 s69, v253, 29
	v_readlane_b32 s70, v253, 30
	v_readlane_b32 s71, v253, 31
	v_readlane_b32 s72, v253, 32
	v_readlane_b32 s73, v253, 33
	s_branch .LBB0_311

; __device__ __forceinline__ void rwkv_sample_task(const Params& p, int s, int h) {
;     unsigned char* ws = p.ws;
;     const int lane = threadIdx.x & 63, rr = lane >> 4, cg_ = lane & 15;
;     const int row = MP + s;
;     const h16* ob = (const h16*)(ws + OFF_OPS16) + ((size_t)row * 8 + h) * 6 * 64;
;     f32x4 r4, d4, k4, a4, b4;
;     {
;         const h16x4 hr = *(const h16x4*)(ob + cg_ * 4), hw = *(const h16x4*)(ob + 64 + cg_ * 4), hk = *(const h16x4*)(ob + 128 + cg_ * 4),
;                     ha = *(const h16x4*)(ob + 256 + cg_ * 4), hb = *(const h16x4*)(ob + 320 + cg_ * 4);
; #pragma unroll
;         for (int j = 0; j < 4; ++j) { r4[j] = (float)hr[j]; d4[j] = __expf((float)hw[j]); k4[j] = (float)hk[j]; a4[j] = (float)ha[j]; b4[j] = (float)hb[j]; }
;     }
;     const float rk = ((const float*)(ws + OFF_RKS))[(size_t)row * 8 + h];
;     const float* S0 = p.in[6] + ((size_t)s * 8 + h) * 4096;
; __device__ __forceinline__ void p3_scan(const Params& p, LAS unsigned char* lds) {
;     ...
;     const int wave = threadIdx.x >> 6;
;     for (int i = blockIdx.x * 8 + wave; i < MS * 8; i += gridDim.x * 8) rwkv_sample_task(p, i >> 3, i & 7);
.LBB0_360:
	s_movk_i32 s0, 0x400
	v_subrev_u32_e32 v2, 0x200, v130
	v_cmp_gt_u32_e32 vcc, 0x400, v2
	s_cmp_eq_u32 s101, 1
	s_cselect_b64 s[98:99], -1, 0
	s_and_b64 vcc, vcc, s[98:99]
	v_mov_b32_e32 v3, 0x7fff0000
	v_cndmask_b32_e32 v143, v3, v2, vcc
	s_cmpk_eq_i32 s33, 0x100
	s_cselect_b64 s[98:99], -1, 0
	v_cndmask_b32_e64 v143, v130, v143, s[98:99]
	v_cmp_gt_i32_e32 vcc, s0, v143
	s_and_saveexec_b64 s[38:39], vcc
	v_readlane_b32 s48, v253, 20
	v_readlane_b32 s49, v253, 21
	v_readlane_b32 s50, v253, 22
	v_readlane_b32 s51, v253, 23
	v_readlane_b32 s60, v253, 32
	v_readlane_b32 s61, v253, 33
	v_readlane_b32 s62, v253, 34
	v_readlane_b32 s63, v253, 35
	v_readlane_b32 s52, v253, 24
	v_readlane_b32 s53, v253, 25
	v_readlane_b32 s54, v253, 26
	v_readlane_b32 s55, v253, 27
	v_readlane_b32 s56, v253, 28
	v_readlane_b32 s57, v253, 29
	v_readlane_b32 s58, v253, 30
	v_readlane_b32 s59, v253, 31
	s_cbranch_execz .LBB0_363
	s_waitcnt vmcnt(5)
	v_mbcnt_hi_u32_b32 v1, -1, v225
	v_and_b32_e32 v3, 64, v1
	v_add_u32_e32 v3, 64, v3
	s_waitcnt vmcnt(4)
	v_xor_b32_e32 v5, 1, v1
	v_cmp_lt_i32_e64 s[0:1], v5, v3
	v_bfe_u32 v54, v132, 6, 3
	v_mov_b32_e32 v53, 0
	v_cndmask_b32_e64 v5, v1, v5, s[0:1]
	v_lshlrev_b32_e32 v55, 2, v5
	v_xor_b32_e32 v5, 2, v1
	v_cmp_lt_i32_e64 s[0:1], v5, v3
	v_lshlrev_b32_e32 v0, 6, v144
	v_or_b32_e32 v30, 60, v146
	v_cndmask_b32_e64 v5, v1, v5, s[0:1]
	v_lshlrev_b32_e32 v57, 2, v5
	v_xor_b32_e32 v5, 4, v1
	v_cmp_lt_i32_e64 s[0:1], v5, v3
	v_lshl_add_u64 v[34:35], s[62:63], 0, v[52:53]
	v_or_b32_e32 v2, 0x100, v0
	v_cndmask_b32_e64 v5, v1, v5, s[0:1]
	v_lshlrev_b32_e32 v129, 2, v5
	v_xor_b32_e32 v5, 8, v1
	v_cmp_lt_i32_e64 s[0:1], v5, v3
	v_or_b32_e32 v4, 0x200, v0
	v_or_b32_e32 v6, 0x300, v0
	v_cndmask_b32_e64 v5, v1, v5, s[0:1]
	v_lshlrev_b32_e32 v135, 2, v5
	v_xor_b32_e32 v5, 16, v1
	v_cmp_lt_i32_e64 s[0:1], v5, v3
	s_waitcnt vmcnt(3)
	v_or_b32_e32 v8, 0x400, v0
	v_or_b32_e32 v10, 0x500, v0
	v_cndmask_b32_e64 v5, v1, v5, s[0:1]
	v_lshlrev_b32_e32 v137, 2, v5
	v_xor_b32_e32 v5, 32, v1
	v_cmp_lt_i32_e64 s[0:1], v5, v3
	s_waitcnt vmcnt(2)
	v_or_b32_e32 v12, 0x600, v0
	v_or_b32_e32 v14, 0x700, v0
	v_cndmask_b32_e64 v1, v1, v5, s[0:1]
	v_lshlrev_b32_e32 v139, 2, v1
	v_lshlrev_b32_e32 v1, 6, v54
	s_mov_b64 s[0:1], s[76:77]
	v_readlane_b32 s64, v253, 4
	v_or3_b32 v1, v1, v36, v144
	v_readlane_b32 s76, v253, 16
	v_readlane_b32 s77, v253, 17
	s_waitcnt vmcnt(1)
	v_or_b32_e32 v16, 0x800, v0
	v_or_b32_e32 v18, 0x900, v0
	v_lshl_add_u64 v[58:59], s[76:77], 0, v[52:53]
	s_mov_b64 s[76:77], s[0:1]
	s_mov_b64 s[0:1], 0x546b100
	v_lshlrev_b32_e32 v52, 1, v1
	s_waitcnt vmcnt(0)
	v_or_b32_e32 v20, 0xa00, v0
	v_or_b32_e32 v22, 0xb00, v0
	v_or_b32_e32 v24, 0xc00, v0
	v_or_b32_e32 v26, 0xd00, v0
	v_or_b32_e32 v28, 0xe00, v0
	v_lshlrev_b32_e32 v32, 6, v30
	s_add_u32 s40, s82, 0x1aec800
	v_lshl_add_u64 v[60:61], v[34:35], 0, s[0:1]
	v_lshl_add_u64 v[62:63], s[62:63], 0, v[52:53]
	s_mov_b64 s[0:1], 0x2080000
	v_lshlrev_b32_e32 v52, 2, v1
	v_cmp_eq_u32_e32 vcc, 0, v131
	v_cmp_eq_u32_e64 s[4:5], 1, v131
	v_cmp_eq_u32_e64 s[6:7], 2, v131
	s_movk_i32 s3, 0x300
	v_cmp_eq_u32_e64 s[8:9], 3, v131
	v_cmp_eq_u32_e64 s[10:11], 4, v131
	v_cmp_eq_u32_e64 s[12:13], 5, v131
	v_cmp_eq_u32_e64 s[14:15], 6, v131
	v_cmp_eq_u32_e64 s[16:17], 7, v131
	v_cmp_eq_u32_e64 s[18:19], 8, v131
	v_cmp_eq_u32_e64 s[20:21], 9, v131
	v_cmp_eq_u32_e64 s[22:23], 10, v131
	v_cmp_eq_u32_e64 s[24:25], 11, v131
	v_cmp_eq_u32_e64 s[26:27], 12, v131
	v_cmp_eq_u32_e64 s[28:29], 13, v131
	v_cmp_eq_u32_e64 s[30:31], 14, v131
	v_cmp_eq_u32_e64 s[34:35], 15, v131
	v_lshlrev_b32_e32 v56, 12, v54
	s_addc_u32 s41, s83, 0
	v_lshl_add_u64 v[64:65], v[62:63], 0, s[0:1]
	v_lshl_add_u64 v[66:67], s[48:49], 0, v[52:53]
	v_lshl_add_u64 v[68:69], s[50:51], 0, v[52:53]
	s_mov_b64 s[42:43], 0
	v_lshlrev_b32_e32 v52, 1, v36
	v_lshlrev_b32_e32 v70, 1, v144
	v_lshlrev_b32_e32 v72, 2, v0
	v_lshlrev_b32_e32 v74, 2, v2
	v_lshlrev_b32_e32 v76, 2, v4
	v_lshlrev_b32_e32 v78, 2, v6
	v_lshlrev_b32_e32 v80, 2, v8
	v_lshlrev_b32_e32 v82, 2, v10
	v_lshlrev_b32_e32 v84, 2, v12
	v_lshlrev_b32_e32 v86, 2, v14
	v_lshlrev_b32_e32 v88, 2, v16
	v_lshlrev_b32_e32 v90, 2, v18
	v_lshlrev_b32_e32 v92, 2, v20
	v_lshlrev_b32_e32 v94, 2, v22
	v_lshlrev_b32_e32 v96, 2, v24
	v_lshlrev_b32_e32 v98, 2, v26
	v_lshlrev_b32_e32 v100, 2, v28
	v_lshlrev_b32_e32 v102, 1, v30
	v_lshlrev_b32_e32 v104, 2, v32
	v_mov_b32_e32 v141, 0x3a27c5ac
	s_mov_b32 s44, 0x800000
	s_movk_i32 s45, 0x3ff
	s_nop 0
	v_readlane_b32 s65, v253, 5
	v_readlane_b32 s66, v253, 6
	v_readlane_b32 s67, v253, 7
	v_readlane_b32 s68, v253, 8
	v_readlane_b32 s69, v253, 9
	v_readlane_b32 s70, v253, 10
	v_readlane_b32 s71, v253, 11
	v_readlane_b32 s72, v253, 12
	v_readlane_b32 s73, v253, 13
	v_readlane_b32 s74, v253, 14
	v_readlane_b32 s75, v253, 15
	v_readlane_b32 s78, v253, 18
	v_readlane_b32 s79, v253, 19

; __device__ __forceinline__ void p3_scan(const Params& p, LAS unsigned char* lds) {
;     ...
;     for (int i = blockIdx.x * 8 + wave; i < MS * 8; i += gridDim.x * 8) rwkv_sample_task(p, i >> 3, i & 7);
; }
; __global__ void __launch_bounds__(512, 2) hymba_fwd(Params p) {
;     ...
;     xcd_barrier(xb);
.LBB0_363:
	s_or_b64 exec, exec, s[38:39]
	s_cmp_eq_u32 s101, 1
	s_cbranch_scc0 .Lsf_cont
	s_mov_b32 s101, 2
	v_lshrrev_b32_e32 v146, 4, v132
	s_branch .LBB0_289
.Lsf_cont:
	s_waitcnt vmcnt(0)
	s_barrier
	v_readfirstlane_b32 s97, v132
	s_cmp_eq_u32 s97, 64
	s_cbranch_scc0 .Linvw_3
	buffer_inv sc1
	s_waitcnt vmcnt(0)
.Linvw_3:
	s_mov_b64 s[0:1], exec
	v_readlane_b32 s4, v253, 2
	v_readlane_b32 s5, v253, 3
	s_and_b64 s[4:5], s[0:1], s[4:5]
	s_mov_b64 exec, s[4:5]
	s_cbranch_execz .LBB0_382
	s_cmpk_lg_i32 s33, 0x100
	s_cbranch_scc1 .Lps_g_orig
	v_mov_b32_e32 v4, 0x1b719c0
	v_mov_b32_e32 v5, 1
	global_atomic_add v4, v5, s[82:83]
	s_and_b32 s97, s2, 7
	s_lshl_b32 s97, s97, 6
	s_add_i32 s97, s97, 0x1b6e908
	v_mov_b32_e32 v4, s97
	global_atomic_add v4, v5, s[82:83]
